# v30 + nt policy on EpiScaleT output stores (KVT)
# baseline (speedup 1.0000x reference)
; #define PG8_LAS __attribute__((address_space(3)))
; __device__ __forceinline__ unsigned cvt_pk_bf16(float lo, float hi) { unsigned r; asm volatile("v_cvt_pk_bf16_f32 %0, %1, %2" : "=v"(r) : "v"(lo), "v"(hi)); return r; }
;     __device__ __forceinline__ void operator()(const f32x4 (&acc)[2][2][4][2], const Unit& u, int wr, int wc, int fr, int fq, PG8_LAS unsigned char* lds, int wid, int lane) const {
;     ...
;         asm volatile("s_waitcnt lgkmcnt(0)" ::: "memory"); __builtin_amdgcn_s_barrier(); asm volatile("" ::: "memory");
;         f32x4 cr[2][2];
; #pragma unroll
;         for (int bj = 0; bj < 2; ++bj)
; #pragma unroll
;             for (int n = 0; n < 2; ++n) cr[bj][n] = *(const PG8_LAS f32x4*)(tbl + bj * HALF + wc * 32 + 8 * fq + 4 * n);
;         bf16_t* obase = O + (size_t)(u.pm * BM + wr * 64 + (lane >> 2)) * ldc + u.pn * BM + wc * 32 + 8 * (lane & 3);
; #pragma unroll
;         for (int ai = 0; ai < 2; ++ai)
; #pragma unroll
;             for (int m = 0; m < 4; ++m) {
; #pragma unroll
;                 for (int bj = 0; bj < 2; ++bj) { const f32x4 v0 = acc[ai][bj][m][0] * cr[bj][0], v1 = acc[ai][bj][m][1] * cr[bj][1];
;                     u32x4 w; w.x = cvt_pk_bf16(v0[0], v0[1]); w.y = cvt_pk_bf16(v0[2], v0[3]); w.z = cvt_pk_bf16(v1[0], v1[1]); w.w = cvt_pk_bf16(v1[2], v1[3]);
;                     *(PG8_LAS u32x4*)(st + fr * 80 + fq * 16) = w;
;                     const u32x4 x = *(const PG8_LAS u32x4*)(st + (lane >> 2) * 80 + (lane & 3) * 16);
;                     *(u32x4*)(obase + (size_t)(ai * HALF + m * 16) * ldc + bj * HALF) = x; } }
.LBB0_475:
	s_or_b64 exec, exec, s[40:41]
	s_waitcnt lgkmcnt(0)
	s_barrier
	ds_read_b128 v[148:151], v168
	ds_read_b128 v[144:147], v168 offset:16
	ds_read_b128 v[140:143], v168 offset:512
	ds_read_b128 v[136:139], v168 offset:528
	v_lshl_add_u32 v171, s77, 8, v166
	v_ashrrev_i32_e32 v172, 31, v171
	v_mul_lo_u32 v174, s26, v172
	v_mul_lo_u32 v175, s27, v171
	v_mad_u64_u32 v[172:173], s[0:1], s26, v171, 0
	v_add3_u32 v173, v173, v174, v175
	s_waitcnt lgkmcnt(0)
	v_pk_mul_f32 v[174:175], v[130:131], v[146:147]
	v_pk_mul_f32 v[130:131], v[128:129], v[144:145]
	v_readlane_b32 s0, v252, 45
	v_pk_mul_f32 v[134:135], v[134:135], v[150:151]
	v_pk_mul_f32 v[132:133], v[132:133], v[148:149]
	v_readlane_b32 s1, v252, 46
	v_cvt_pk_bf16_f32 v128, v132, v133
	v_cvt_pk_bf16_f32 v129, v134, v135
	v_cvt_pk_bf16_f32 v130, v130, v131
	v_cvt_pk_bf16_f32 v131, v174, v175
	ds_write_b128 v169, v[128:131]
	ds_read_b128 v[128:131], v170
	v_lshl_add_u64 v[172:173], v[172:173], 1, s[0:1]
	s_ashr_i32 s39, s38, 31
	v_lshl_add_u64 v[132:133], s[38:39], 1, v[172:173]
	v_lshl_add_u64 v[132:133], v[132:133], 0, s[20:21]
	v_lshl_add_u64 v[132:133], v[132:133], 0, v[0:1]
	s_waitcnt lgkmcnt(0)
	global_store_dwordx4 v[132:133], v[128:131], off nt
	v_pk_mul_f32 v[126:127], v[126:127], v[142:143]
	v_pk_mul_f32 v[124:125], v[124:125], v[140:141]
	v_pk_mul_f32 v[128:129], v[122:123], v[138:139]
	v_pk_mul_f32 v[122:123], v[120:121], v[136:137]
	v_cvt_pk_bf16_f32 v120, v124, v125
	v_cvt_pk_bf16_f32 v121, v126, v127
	v_pk_mul_f32 v[118:119], v[118:119], v[150:151]
	v_cvt_pk_bf16_f32 v122, v122, v123
	v_cvt_pk_bf16_f32 v123, v128, v129
	ds_write_b128 v169, v[120:123]
	ds_read_b128 v[120:123], v170
	v_pk_mul_f32 v[116:117], v[116:117], v[148:149]
	v_pk_mul_f32 v[110:111], v[110:111], v[142:143]
	v_pk_mul_f32 v[108:109], v[108:109], v[140:141]
	v_pk_mul_f32 v[102:103], v[102:103], v[150:151]
	s_waitcnt lgkmcnt(0)
	global_store_dwordx4 v[132:133], v[120:123], off offset:256 nt
	v_pk_mul_f32 v[100:101], v[100:101], v[148:149]
	v_pk_mul_f32 v[94:95], v[94:95], v[142:143]
	v_pk_mul_f32 v[120:121], v[114:115], v[146:147]
	v_pk_mul_f32 v[114:115], v[112:113], v[144:145]
	v_cvt_pk_bf16_f32 v112, v116, v117
	v_cvt_pk_bf16_f32 v113, v118, v119
	v_lshl_add_u64 v[116:117], v[132:133], 0, s[54:55]
	v_cvt_pk_bf16_f32 v114, v114, v115
	v_cvt_pk_bf16_f32 v115, v120, v121
	ds_write_b128 v169, v[112:115]
	ds_read_b128 v[112:115], v170
	v_pk_mul_f32 v[92:93], v[92:93], v[140:141]
	v_pk_mul_f32 v[86:87], v[86:87], v[150:151]
	v_pk_mul_f32 v[84:85], v[84:85], v[148:149]
	v_pk_mul_f32 v[78:79], v[78:79], v[142:143]
	s_waitcnt lgkmcnt(0)
	global_store_dwordx4 v[116:117], v[112:115], off nt
	v_pk_mul_f32 v[76:77], v[76:77], v[140:141]
	v_pk_mul_f32 v[70:71], v[70:71], v[150:151]
	v_pk_mul_f32 v[112:113], v[106:107], v[138:139]
	v_pk_mul_f32 v[106:107], v[104:105], v[136:137]
	v_cvt_pk_bf16_f32 v104, v108, v109
	v_cvt_pk_bf16_f32 v105, v110, v111
	v_pk_mul_f32 v[68:69], v[68:69], v[148:149]
	v_cvt_pk_bf16_f32 v106, v106, v107
	v_cvt_pk_bf16_f32 v107, v112, v113
	ds_write_b128 v169, v[104:107]
	ds_read_b128 v[104:107], v170
	v_pk_mul_f32 v[62:63], v[62:63], v[142:143]
	v_pk_mul_f32 v[60:61], v[60:61], v[140:141]
	v_pk_mul_f32 v[54:55], v[54:55], v[150:151]
	v_pk_mul_f32 v[52:53], v[52:53], v[148:149]
	s_waitcnt lgkmcnt(0)
	global_store_dwordx4 v[116:117], v[104:107], off offset:256 nt
	v_pk_mul_f32 v[46:47], v[46:47], v[142:143]
	v_pk_mul_f32 v[44:45], v[44:45], v[140:141]
	v_pk_mul_f32 v[104:105], v[98:99], v[146:147]
	v_pk_mul_f32 v[98:99], v[96:97], v[144:145]
	v_cvt_pk_bf16_f32 v96, v100, v101
	v_cvt_pk_bf16_f32 v97, v102, v103
	v_lshl_add_u64 v[100:101], v[116:117], 0, s[54:55]
	v_cvt_pk_bf16_f32 v98, v98, v99
	v_cvt_pk_bf16_f32 v99, v104, v105
	ds_write_b128 v169, v[96:99]
	ds_read_b128 v[96:99], v170
	v_pk_mul_f32 v[38:39], v[38:39], v[150:151]
	v_pk_mul_f32 v[36:37], v[36:37], v[148:149]
	v_pk_mul_f32 v[30:31], v[30:31], v[142:143]
	v_pk_mul_f32 v[28:29], v[28:29], v[140:141]
	s_waitcnt lgkmcnt(0)
	global_store_dwordx4 v[100:101], v[96:99], off nt
	v_pk_mul_f32 v[22:23], v[22:23], v[150:151]
	v_pk_mul_f32 v[20:21], v[20:21], v[148:149]
	v_pk_mul_f32 v[96:97], v[90:91], v[138:139]
	v_pk_mul_f32 v[90:91], v[88:89], v[136:137]
	v_cvt_pk_bf16_f32 v88, v92, v93
	v_cvt_pk_bf16_f32 v89, v94, v95
	v_pk_mul_f32 v[14:15], v[14:15], v[142:143]
	v_cvt_pk_bf16_f32 v90, v90, v91
	v_cvt_pk_bf16_f32 v91, v96, v97
	ds_write_b128 v169, v[88:91]
	ds_read_b128 v[88:91], v170
	v_pk_mul_f32 v[12:13], v[12:13], v[140:141]
	s_and_b64 vcc, exec, s[4:5]
	s_mov_b64 s[0:1], -1
	s_waitcnt lgkmcnt(0)
; #define PG8_LAS __attribute__((address_space(3)))
; __device__ __forceinline__ unsigned cvt_pk_bf16(float lo, float hi) { unsigned r; asm volatile("v_cvt_pk_bf16_f32 %0, %1, %2" : "=v"(r) : "v"(lo), "v"(hi)); return r; }
;     __device__ __forceinline__ void operator()(const f32x4 (&acc)[2][2][4][2], const Unit& u, int wr, int wc, int fr, int fq, PG8_LAS unsigned char* lds, int wid, int lane) const {
;     ...
;         asm volatile("s_waitcnt lgkmcnt(0)" ::: "memory"); __builtin_amdgcn_s_barrier(); asm volatile("" ::: "memory");
;         f32x4 cr[2][2];
; #pragma unroll
;         for (int bj = 0; bj < 2; ++bj)
; #pragma unroll
;             for (int n = 0; n < 2; ++n) cr[bj][n] = *(const PG8_LAS f32x4*)(tbl + bj * HALF + wc * 32 + 8 * fq + 4 * n);
;         bf16_t* obase = O + (size_t)(u.pm * BM + wr * 64 + (lane >> 2)) * ldc + u.pn * BM + wc * 32 + 8 * (lane & 3);
; #pragma unroll
;         for (int ai = 0; ai < 2; ++ai)
; #pragma unroll
;             for (int m = 0; m < 4; ++m) {
; #pragma unroll
;                 for (int bj = 0; bj < 2; ++bj) { const f32x4 v0 = acc[ai][bj][m][0] * cr[bj][0], v1 = acc[ai][bj][m][1] * cr[bj][1];
;                     u32x4 w; w.x = cvt_pk_bf16(v0[0], v0[1]); w.y = cvt_pk_bf16(v0[2], v0[3]); w.z = cvt_pk_bf16(v1[0], v1[1]); w.w = cvt_pk_bf16(v1[2], v1[3]);
;                     *(PG8_LAS u32x4*)(st + fr * 80 + fq * 16) = w;
;                     const u32x4 x = *(const PG8_LAS u32x4*)(st + (lane >> 2) * 80 + (lane & 3) * 16);
;                     *(u32x4*)(obase + (size_t)(ai * HALF + m * 16) * ldc + bj * HALF) = x; } }
	global_store_dwordx4 v[100:101], v[88:91], off offset:256 nt
	s_nop 1
	v_pk_mul_f32 v[88:89], v[82:83], v[146:147]
	v_pk_mul_f32 v[82:83], v[80:81], v[144:145]
	v_cvt_pk_bf16_f32 v80, v84, v85
	v_cvt_pk_bf16_f32 v81, v86, v87
	v_lshl_add_u64 v[84:85], v[100:101], 0, s[54:55]
	v_cvt_pk_bf16_f32 v82, v82, v83
	v_cvt_pk_bf16_f32 v83, v88, v89
	ds_write_b128 v169, v[80:83]
	ds_read_b128 v[80:83], v170
	s_waitcnt lgkmcnt(0)
	global_store_dwordx4 v[84:85], v[80:83], off nt
	s_nop 1
	v_pk_mul_f32 v[80:81], v[74:75], v[138:139]
	v_pk_mul_f32 v[74:75], v[72:73], v[136:137]
	v_cvt_pk_bf16_f32 v72, v76, v77
	v_cvt_pk_bf16_f32 v73, v78, v79
	s_nop 0
	v_cvt_pk_bf16_f32 v74, v74, v75
	v_cvt_pk_bf16_f32 v75, v80, v81
	ds_write_b128 v169, v[72:75]
	ds_read_b128 v[72:75], v170
	s_waitcnt lgkmcnt(0)
	global_store_dwordx4 v[84:85], v[72:75], off offset:256 nt
	s_nop 1
	v_pk_mul_f32 v[72:73], v[66:67], v[146:147]
	v_pk_mul_f32 v[66:67], v[64:65], v[144:145]
	v_cvt_pk_bf16_f32 v64, v68, v69
	v_cvt_pk_bf16_f32 v65, v70, v71
	v_lshl_add_u64 v[68:69], v[84:85], 0, s[16:17]
	v_cvt_pk_bf16_f32 v66, v66, v67
	v_cvt_pk_bf16_f32 v67, v72, v73
	ds_write_b128 v169, v[64:67]
	ds_read_b128 v[64:67], v170
	s_waitcnt lgkmcnt(0)
	global_store_dwordx4 v[68:69], v[64:67], off nt
	s_nop 1
	v_pk_mul_f32 v[64:65], v[58:59], v[138:139]
	v_pk_mul_f32 v[58:59], v[56:57], v[136:137]
	v_cvt_pk_bf16_f32 v56, v60, v61
	v_cvt_pk_bf16_f32 v57, v62, v63
	s_nop 0
	v_cvt_pk_bf16_f32 v58, v58, v59
	v_cvt_pk_bf16_f32 v59, v64, v65
	ds_write_b128 v169, v[56:59]
	ds_read_b128 v[56:59], v170
	s_waitcnt lgkmcnt(0)
	global_store_dwordx4 v[68:69], v[56:59], off offset:256 nt
	s_nop 1
	v_pk_mul_f32 v[56:57], v[50:51], v[146:147]
	v_pk_mul_f32 v[50:51], v[48:49], v[144:145]
	v_cvt_pk_bf16_f32 v48, v52, v53
	v_cvt_pk_bf16_f32 v49, v54, v55
	v_lshl_add_u64 v[52:53], v[68:69], 0, s[54:55]
	v_cvt_pk_bf16_f32 v50, v50, v51
	v_cvt_pk_bf16_f32 v51, v56, v57
	ds_write_b128 v169, v[48:51]
	ds_read_b128 v[48:51], v170
	s_waitcnt lgkmcnt(0)
	global_store_dwordx4 v[52:53], v[48:51], off nt
	s_nop 1
	v_pk_mul_f32 v[48:49], v[42:43], v[138:139]
	v_pk_mul_f32 v[42:43], v[40:41], v[136:137]
	v_cvt_pk_bf16_f32 v40, v44, v45
	v_cvt_pk_bf16_f32 v41, v46, v47
	s_nop 0
	v_cvt_pk_bf16_f32 v42, v42, v43
	v_cvt_pk_bf16_f32 v43, v48, v49
	ds_write_b128 v169, v[40:43]
	ds_read_b128 v[40:43], v170
	s_waitcnt lgkmcnt(0)
	global_store_dwordx4 v[52:53], v[40:43], off offset:256 nt
	s_nop 1
	v_pk_mul_f32 v[40:41], v[34:35], v[146:147]
	v_pk_mul_f32 v[34:35], v[32:33], v[144:145]
	v_cvt_pk_bf16_f32 v32, v36, v37
	v_cvt_pk_bf16_f32 v33, v38, v39
	v_lshl_add_u64 v[36:37], v[52:53], 0, s[54:55]
	v_cvt_pk_bf16_f32 v34, v34, v35
	v_cvt_pk_bf16_f32 v35, v40, v41
	ds_write_b128 v169, v[32:35]
	ds_read_b128 v[32:35], v170
	s_waitcnt lgkmcnt(0)
	global_store_dwordx4 v[36:37], v[32:35], off nt
	s_nop 1
	v_pk_mul_f32 v[32:33], v[26:27], v[138:139]
	v_pk_mul_f32 v[26:27], v[24:25], v[136:137]
	v_cvt_pk_bf16_f32 v24, v28, v29
	v_cvt_pk_bf16_f32 v25, v30, v31
	s_nop 0
	v_cvt_pk_bf16_f32 v26, v26, v27
	v_cvt_pk_bf16_f32 v27, v32, v33
	ds_write_b128 v169, v[24:27]
	ds_read_b128 v[24:27], v170
	s_waitcnt lgkmcnt(0)
	global_store_dwordx4 v[36:37], v[24:27], off offset:256 nt
	s_nop 1
	v_pk_mul_f32 v[24:25], v[18:19], v[146:147]
	v_pk_mul_f32 v[18:19], v[16:17], v[144:145]
	v_cvt_pk_bf16_f32 v16, v20, v21
	v_cvt_pk_bf16_f32 v17, v22, v23
	v_lshl_add_u64 v[20:21], v[36:37], 0, s[54:55]
	v_cvt_pk_bf16_f32 v18, v18, v19
	v_cvt_pk_bf16_f32 v19, v24, v25
	ds_write_b128 v169, v[16:19]
	ds_read_b128 v[16:19], v170
	s_waitcnt lgkmcnt(0)
	global_store_dwordx4 v[20:21], v[16:19], off nt
	s_nop 1
	v_pk_mul_f32 v[16:17], v[10:11], v[138:139]
	v_pk_mul_f32 v[10:11], v[8:9], v[136:137]
	v_cvt_pk_bf16_f32 v8, v12, v13
	v_cvt_pk_bf16_f32 v9, v14, v15
	s_nop 0
	v_cvt_pk_bf16_f32 v10, v10, v11
	v_cvt_pk_bf16_f32 v11, v16, v17
	ds_write_b128 v169, v[8:11]
	ds_read_b128 v[8:11], v170
	s_waitcnt lgkmcnt(0)
	global_store_dwordx4 v[20:21], v[8:11], off offset:256 nt
	s_cbranch_vccnz .LBB0_455
	s_andn2_b64 vcc, exec, s[10:11]
	s_cbranch_vccnz .LBB0_454
	s_barrier
	s_branch .LBB0_454
